# stack15 + loop-edge edit: the P.V loop's wave-uniform first-pass flag from s_cmp + s_cselect_b64 vcc instead of v_cndmask + v_cmp
# speedup vs baseline: 1.0131x; 1.0131x over previous
; __device__ __forceinline__ void sattn_unit(const bf16* Qb, const bf16* Kb, const bf16* Vb, const float* ck, const float* cv, const int* pt, bf16* MIX, const float* sg, float lam,
;                                            int s, int h, int c0, LAS unsigned char* lds, int tid_in) {
;     ...
;         for (int k0 = 0; k0 < 64; k0 += 32) { f32x4 vv[16];
; #pragma unroll
;             for (int k = 0; k < 16; ++k) vv[k] = *(const f32x4*)(vp + (size_t)(k0 + 2 * k) * NH * 128);
.LBB0_499:
	s_lshl_b32 s6, s46, 9
	v_or_b32_e32 v169, s46, v134
	s_cmp_eq_u32 s46, 0
	s_cselect_b64 vcc, 0, exec
	v_lshl_add_u32 v169, v169, 5, s21
	s_cbranch_scc1 .Lmy_sa_pvfma
	v_lshl_add_u64 v[106:107], s[6:7], 2, v[146:147]
	s_movk_i32 s0, 0x2000
	v_add_co_u32_e64 v2, s[0:1], s0, v106
	global_load_dwordx4 v[110:113], v[106:107], off
	s_nop 0
	v_addc_co_u32_e64 v3, s[0:1], 0, v107, s[0:1]
	s_movk_i32 s0, 0x4000
	global_load_dwordx4 v[114:117], v[2:3], off offset:-4096
	global_load_dwordx4 v[118:121], v[2:3], off
	v_add_co_u32_e64 v2, s[0:1], s0, v106
	s_nop 0
	s_nop 0
	v_addc_co_u32_e64 v3, s[0:1], 0, v107, s[0:1]
	global_load_dwordx4 v[122:125], v[2:3], off offset:-4096
	global_load_dwordx4 v[126:129], v[2:3], off
	s_movk_i32 s0, 0x6000
	v_add_co_u32_e64 v6, s[0:1], s0, v106
	s_nop 0
	s_nop 0
	v_addc_co_u32_e64 v7, s[0:1], 0, v107, s[0:1]
	s_mov_b32 s0, 0x8000
	s_nop 0
	v_add_co_u32_e64 v14, s[0:1], s0, v106
	global_load_dwordx4 v[2:5], v[6:7], off offset:-4096
	s_nop 0
	global_load_dwordx4 v[6:9], v[6:7], off
	v_addc_co_u32_e64 v15, s[0:1], 0, v107, s[0:1]
	s_mov_b32 s0, 0xa000
	s_nop 0
	v_add_co_u32_e64 v248, s[0:1], s0, v106
	global_load_dwordx4 v[10:13], v[14:15], off offset:-4096
	s_nop 0
	global_load_dwordx4 v[14:17], v[14:15], off
	v_addc_co_u32_e64 v249, s[0:1], 0, v107, s[0:1]
	s_mov_b32 s0, 0xc000
	s_nop 0
	v_add_co_u32_e64 v94, s[0:1], s0, v106
	global_load_dwordx4 v[242:245], v[248:249], off offset:-4096
	s_nop 0
	global_load_dwordx4 v[248:251], v[248:249], off
	v_addc_co_u32_e64 v95, s[0:1], 0, v107, s[0:1]
	s_mov_b32 s0, 0xe000
	s_nop 0
	v_add_co_u32_e64 v102, s[0:1], s0, v106
	global_load_dwordx4 v[90:93], v[94:95], off offset:-4096
	s_nop 0
	global_load_dwordx4 v[94:97], v[94:95], off
	v_addc_co_u32_e64 v103, s[0:1], 0, v107, s[0:1]
	s_mov_b32 s0, 0xf000
	s_nop 0
	v_add_co_u32_e64 v106, s[0:1], s0, v106
	global_load_dwordx4 v[98:101], v[102:103], off offset:-4096
	s_nop 0
	global_load_dwordx4 v[102:105], v[102:103], off
	v_addc_co_u32_e64 v107, s[0:1], 0, v107, s[0:1]
	global_load_dwordx4 v[106:109], v[106:107], off
